# attention output tail: the 16 diff_subln_g loads issued together once per unit instead of one per output piece behind vmcnt(0)
# baseline (speedup 1.0000x reference)
; __device__ __forceinline__ void phase_attn(const Params& p, unsigned char* lds) {
;     ...
;         if (cmap == 0) {
;             float sq = 0.f;
; #pragma unroll
;             for (int vb = 0; vb < 4; ++vb)
; #pragma unroll
;                 for (int i = 0; i < 16; ++i) { const float o = ot[vb][i] * inv - lam * ex[(vb * 16 + i) * 256 + qsub * 64 + lane]; ot[vb][i] = o; sq += o * o; }
.LBB0_2029:
	s_or_b64 exec, exec, s[20:21]
	s_waitcnt lgkmcnt(0)
	s_barrier
	s_and_saveexec_b64 s[20:21], s[6:7]
	s_cbranch_execz .LBB0_2019
	ds_read2st64_b32 v[66:67], v161 offset1:4
	v_mov_b32_e32 v128, v48
	ds_read2st64_b32 v[68:69], v161 offset0:8 offset1:12
	s_lshl_b32 s12, s30, 1
	v_mov_b32_e32 v149, v133
	s_waitcnt lgkmcnt(1)
	v_mov_b32_e32 v65, v66
	v_pk_mul_f32 v[70:71], v[128:129], v[64:65]
	v_mov_b32_e32 v128, v49
	v_sub_f32_e32 v48, v70, v71
	ds_read2st64_b32 v[70:71], v161 offset0:16 offset1:20
	v_mov_b32_e32 v65, v67
	v_pk_mul_f32 v[66:67], v[128:129], v[64:65]
	v_mov_b32_e32 v128, v50
	s_waitcnt lgkmcnt(1)
	v_mov_b32_e32 v65, v68
	v_sub_f32_e32 v49, v66, v67
	v_pk_mul_f32 v[66:67], v[128:129], v[64:65]
	v_mov_b32_e32 v128, v51
	v_mov_b32_e32 v65, v69
	v_sub_f32_e32 v50, v66, v67
	v_pk_mul_f32 v[66:67], v[128:129], v[64:65]
	v_mov_b32_e32 v128, v52
	s_waitcnt lgkmcnt(0)
	v_mov_b32_e32 v65, v70
	v_pk_mul_f32 v[68:69], v[128:129], v[64:65]
	v_mov_b32_e32 v128, v53
	v_sub_f32_e32 v51, v68, v69
	ds_read2st64_b32 v[68:69], v161 offset0:24 offset1:28
	v_mov_b32_e32 v65, v71
	v_pk_mul_f32 v[52:53], v[128:129], v[64:65]
	v_mov_b32_e32 v128, v54
	v_sub_f32_e32 v52, v52, v53
	s_waitcnt lgkmcnt(0)
	v_mov_b32_e32 v65, v68
	v_pk_mul_f32 v[70:71], v[128:129], v[64:65]
	v_mov_b32_e32 v128, v55
	v_sub_f32_e32 v53, v70, v71
	ds_read2st64_b32 v[70:71], v161 offset0:32 offset1:36
	v_mov_b32_e32 v65, v69
	v_pk_mul_f32 v[54:55], v[128:129], v[64:65]
	v_mov_b32_e32 v128, v56
	v_sub_f32_e32 v54, v54, v55
	s_waitcnt lgkmcnt(0)
	v_mov_b32_e32 v65, v70
	v_pk_mul_f32 v[68:69], v[128:129], v[64:65]
	v_mov_b32_e32 v128, v57
	v_sub_f32_e32 v55, v68, v69
	ds_read2st64_b32 v[68:69], v161 offset0:40 offset1:44
	v_mov_b32_e32 v65, v71
	v_pk_mul_f32 v[56:57], v[128:129], v[64:65]
	v_mov_b32_e32 v128, v58
	v_sub_f32_e32 v56, v56, v57
	s_waitcnt lgkmcnt(0)
	v_mov_b32_e32 v65, v68
	v_pk_mul_f32 v[70:71], v[128:129], v[64:65]
	v_mov_b32_e32 v128, v59
	v_sub_f32_e32 v57, v70, v71
	ds_read2st64_b32 v[70:71], v161 offset0:48 offset1:52
	v_mov_b32_e32 v65, v69
	v_pk_mul_f32 v[58:59], v[128:129], v[64:65]
	v_mov_b32_e32 v128, v60
	v_sub_f32_e32 v58, v58, v59
	s_waitcnt lgkmcnt(0)
	v_mov_b32_e32 v65, v70
	v_pk_mul_f32 v[68:69], v[128:129], v[64:65]
	v_mov_b32_e32 v128, v61
	v_sub_f32_e32 v59, v68, v69
	ds_read2st64_b32 v[68:69], v161 offset0:56 offset1:60
	v_mov_b32_e32 v65, v71
	v_pk_mul_f32 v[60:61], v[128:129], v[64:65]
	v_mov_b32_e32 v128, v62
	v_sub_f32_e32 v60, v60, v61
	s_waitcnt lgkmcnt(0)
	v_mov_b32_e32 v65, v68
	v_pk_mul_f32 v[70:71], v[128:129], v[64:65]
	v_mov_b32_e32 v128, v63
	v_sub_f32_e32 v61, v70, v71
	ds_read2st64_b32 v[70:71], v161 offset0:64 offset1:68
	v_mov_b32_e32 v65, v69
	v_pk_mul_f32 v[62:63], v[128:129], v[64:65]
	v_mov_b32_e32 v128, v32
	v_sub_f32_e32 v62, v62, v63
	s_waitcnt lgkmcnt(0)
	v_mov_b32_e32 v65, v70
	v_pk_mul_f32 v[68:69], v[128:129], v[64:65]
	v_mov_b32_e32 v128, v33
	v_sub_f32_e32 v32, v68, v69
	ds_read2st64_b32 v[68:69], v161 offset0:72 offset1:76
	v_mov_b32_e32 v65, v71
	v_pk_mul_f32 v[70:71], v[128:129], v[64:65]
	v_mov_b32_e32 v128, v34
	v_sub_f32_e32 v33, v70, v71
	s_waitcnt lgkmcnt(0)
	v_mov_b32_e32 v65, v68
	v_pk_mul_f32 v[70:71], v[128:129], v[64:65]
	v_mov_b32_e32 v128, v35
	v_sub_f32_e32 v34, v70, v71
	ds_read2st64_b32 v[70:71], v161 offset0:80 offset1:84
	v_mov_b32_e32 v65, v69
	v_pk_mul_f32 v[68:69], v[128:129], v[64:65]
	v_mov_b32_e32 v128, v36
	v_sub_f32_e32 v35, v68, v69
	s_waitcnt lgkmcnt(0)
	v_mov_b32_e32 v65, v70
	v_pk_mul_f32 v[68:69], v[128:129], v[64:65]
	v_mov_b32_e32 v128, v37
	v_sub_f32_e32 v36, v68, v69
	ds_read2st64_b32 v[68:69], v161 offset0:88 offset1:92
	v_mov_b32_e32 v65, v71
	v_pk_mul_f32 v[70:71], v[128:129], v[64:65]
	v_mov_b32_e32 v128, v38
	v_sub_f32_e32 v37, v70, v71
	s_waitcnt lgkmcnt(0)
	v_mov_b32_e32 v65, v68
	v_pk_mul_f32 v[70:71], v[128:129], v[64:65]
	v_mov_b32_e32 v128, v39
	v_sub_f32_e32 v38, v70, v71
	ds_read2st64_b32 v[70:71], v161 offset0:96 offset1:100
	v_mov_b32_e32 v65, v69
	v_pk_mul_f32 v[68:69], v[128:129], v[64:65]
	v_mov_b32_e32 v128, v40
	v_sub_f32_e32 v63, v68, v69
	s_waitcnt lgkmcnt(0)
	v_mov_b32_e32 v65, v70
	v_pk_mul_f32 v[68:69], v[128:129], v[64:65]
	v_mov_b32_e32 v128, v41
	v_sub_f32_e32 v39, v68, v69
	ds_read2st64_b32 v[68:69], v161 offset0:104 offset1:108
	v_mov_b32_e32 v65, v71
	v_pk_mul_f32 v[40:41], v[128:129], v[64:65]
	v_mov_b32_e32 v128, v42
	v_sub_f32_e32 v40, v40, v41
	s_waitcnt lgkmcnt(0)
	v_mov_b32_e32 v65, v68
	v_pk_mul_f32 v[70:71], v[128:129], v[64:65]
	v_mov_b32_e32 v128, v43
	v_sub_f32_e32 v41, v70, v71
	ds_read2st64_b32 v[70:71], v161 offset0:112 offset1:116
	v_mov_b32_e32 v65, v69
	v_pk_mul_f32 v[42:43], v[128:129], v[64:65]
	v_mov_b32_e32 v128, v44
	v_sub_f32_e32 v43, v42, v43
	s_waitcnt lgkmcnt(0)
	v_mov_b32_e32 v65, v70
	v_pk_mul_f32 v[68:69], v[128:129], v[64:65]
	v_mov_b32_e32 v128, v45
	v_sub_f32_e32 v42, v68, v69
	ds_read2st64_b32 v[68:69], v161 offset0:120 offset1:124
	v_mov_b32_e32 v65, v71
	v_pk_mul_f32 v[44:45], v[128:129], v[64:65]
	v_mov_b32_e32 v128, v46
	v_sub_f32_e32 v44, v44, v45
	s_waitcnt lgkmcnt(0)
	v_mov_b32_e32 v65, v68
	v_pk_mul_f32 v[70:71], v[128:129], v[64:65]
	v_mov_b32_e32 v128, v47
	v_sub_f32_e32 v45, v70, v71
	ds_read2st64_b32 v[70:71], v161 offset0:128 offset1:132
	v_mov_b32_e32 v65, v69
	v_pk_mul_f32 v[46:47], v[128:129], v[64:65]
	v_mov_b32_e32 v128, v16
	v_sub_f32_e32 v46, v46, v47
	s_waitcnt lgkmcnt(0)
	v_mov_b32_e32 v65, v70
	v_pk_mul_f32 v[68:69], v[128:129], v[64:65]
	v_mov_b32_e32 v128, v17
	ds_read2st64_b32 v[16:17], v161 offset0:136 offset1:140
	v_mov_b32_e32 v65, v71
	ds_read2st64_b32 v[70:71], v161 offset0:144 offset1:148
	v_sub_f32_e32 v47, v68, v69
	v_pk_mul_f32 v[68:69], v[128:129], v[64:65]
	v_mov_b32_e32 v128, v18
	s_waitcnt lgkmcnt(1)
; __device__ __forceinline__ void phase_attn(const Params& p, unsigned char* lds) {
;     ...
;         if (cmap == 0) {
;             float sq = 0.f;
; #pragma unroll
;             for (int vb = 0; vb < 4; ++vb)
; #pragma unroll
;                 for (int i = 0; i < 16; ++i) { const float o = ot[vb][i] * inv - lam * ex[(vb * 16 + i) * 256 + qsub * 64 + lane]; ot[vb][i] = o; sq += o * o; }
	v_mov_b32_e32 v65, v16
	v_sub_f32_e32 v66, v66, v67
	v_sub_f32_e32 v67, v68, v69
	v_pk_mul_f32 v[68:69], v[128:129], v[64:65]
	v_mov_b32_e32 v128, v19
	v_mov_b32_e32 v65, v17
	v_pk_mul_f32 v[16:17], v[128:129], v[64:65]
	v_mov_b32_e32 v128, v20
	s_waitcnt lgkmcnt(0)
	v_mov_b32_e32 v65, v70
	v_sub_f32_e32 v18, v68, v69
	v_sub_f32_e32 v68, v16, v17
	v_pk_mul_f32 v[16:17], v[128:129], v[64:65]
	v_mov_b32_e32 v128, v21
	v_sub_f32_e32 v19, v16, v17
	ds_read2st64_b32 v[16:17], v161 offset0:152 offset1:156
	v_mov_b32_e32 v65, v71
	v_pk_mul_f32 v[20:21], v[128:129], v[64:65]
	v_mov_b32_e32 v128, v22
	v_sub_f32_e32 v20, v20, v21
	s_waitcnt lgkmcnt(0)
	v_mov_b32_e32 v65, v16
	v_pk_mul_f32 v[70:71], v[128:129], v[64:65]
	v_mov_b32_e32 v128, v23
	v_sub_f32_e32 v21, v70, v71
	ds_read2st64_b32 v[70:71], v161 offset0:160 offset1:164
	v_mov_b32_e32 v65, v17
	v_pk_mul_f32 v[16:17], v[128:129], v[64:65]
	v_mov_b32_e32 v128, v24
	v_sub_f32_e32 v23, v16, v17
	s_waitcnt lgkmcnt(0)
	v_mov_b32_e32 v65, v70
	v_pk_mul_f32 v[16:17], v[128:129], v[64:65]
	v_mov_b32_e32 v128, v25
	v_sub_f32_e32 v22, v16, v17
	ds_read2st64_b32 v[16:17], v161 offset0:168 offset1:172
	v_mov_b32_e32 v65, v71
	v_pk_mul_f32 v[24:25], v[128:129], v[64:65]
	v_mov_b32_e32 v128, v26
	v_sub_f32_e32 v24, v24, v25
	s_waitcnt lgkmcnt(0)
	v_mov_b32_e32 v65, v16
	v_pk_mul_f32 v[70:71], v[128:129], v[64:65]
	v_mov_b32_e32 v128, v27
	v_sub_f32_e32 v25, v70, v71
	ds_read2st64_b32 v[70:71], v161 offset0:176 offset1:180
	v_mov_b32_e32 v65, v17
	v_pk_mul_f32 v[16:17], v[128:129], v[64:65]
	v_mov_b32_e32 v128, v28
	v_sub_f32_e32 v27, v16, v17
	s_waitcnt lgkmcnt(0)
	v_mov_b32_e32 v65, v70
	v_pk_mul_f32 v[16:17], v[128:129], v[64:65]
	v_mov_b32_e32 v128, v29
	v_sub_f32_e32 v26, v16, v17
	ds_read2st64_b32 v[16:17], v161 offset0:184 offset1:188
	v_mov_b32_e32 v65, v71
	v_pk_mul_f32 v[28:29], v[128:129], v[64:65]
	v_mov_b32_e32 v128, v30
	v_sub_f32_e32 v28, v28, v29
	s_waitcnt lgkmcnt(0)
	v_mov_b32_e32 v65, v16
	v_pk_mul_f32 v[70:71], v[128:129], v[64:65]
	v_mov_b32_e32 v128, v31
	v_sub_f32_e32 v29, v70, v71
	ds_read2st64_b32 v[70:71], v161 offset0:192 offset1:196
	v_mov_b32_e32 v65, v17
	v_pk_mul_f32 v[16:17], v[128:129], v[64:65]
	v_mov_b32_e32 v128, v0
	v_sub_f32_e32 v30, v16, v17
	s_waitcnt lgkmcnt(0)
	v_mov_b32_e32 v65, v70
	v_pk_mul_f32 v[16:17], v[128:129], v[64:65]
	v_mov_b32_e32 v128, v1
	ds_read2st64_b32 v[0:1], v161 offset0:200 offset1:204
	v_mov_b32_e32 v65, v71
	v_sub_f32_e32 v31, v16, v17
	v_pk_mul_f32 v[16:17], v[128:129], v[64:65]
	v_mov_b32_e32 v128, v2
	s_waitcnt lgkmcnt(0)
	v_mov_b32_e32 v65, v0
	v_sub_f32_e32 v69, v16, v17
	v_pk_mul_f32 v[16:17], v[128:129], v[64:65]
	v_mov_b32_e32 v128, v3
	ds_read2st64_b32 v[2:3], v161 offset0:208 offset1:212
	v_mov_b32_e32 v65, v1
	v_pk_mul_f32 v[0:1], v[128:129], v[64:65]
	v_mov_b32_e32 v128, v4
	v_sub_f32_e32 v72, v0, v1
	s_waitcnt lgkmcnt(0)
	v_mov_b32_e32 v65, v2
	v_pk_mul_f32 v[0:1], v[128:129], v[64:65]
	v_mov_b32_e32 v128, v5
	v_sub_f32_e32 v71, v0, v1
	ds_read2st64_b32 v[0:1], v161 offset0:216 offset1:220
	v_mov_b32_e32 v65, v3
	v_pk_mul_f32 v[2:3], v[128:129], v[64:65]
	v_mov_b32_e32 v128, v6
	v_sub_f32_e32 v73, v2, v3
	s_waitcnt lgkmcnt(0)
	v_mov_b32_e32 v65, v0
	v_pk_mul_f32 v[2:3], v[128:129], v[64:65]
	v_mov_b32_e32 v128, v7
	ds_read2st64_b32 v[6:7], v161 offset0:224 offset1:228
	v_mov_b32_e32 v65, v1
	v_pk_mul_f32 v[0:1], v[128:129], v[64:65]
	v_mov_b32_e32 v128, v8
	v_mov_b32_e32 v4, v2
	s_waitcnt lgkmcnt(0)
	v_mov_b32_e32 v65, v6
	v_mov_b32_e32 v5, v0
	v_mov_b32_e32 v0, v3
	v_pk_mul_f32 v[2:3], v[128:129], v[64:65]
	v_mov_b32_e32 v128, v9
	ds_read2st64_b32 v[8:9], v161 offset0:232 offset1:236
	v_mov_b32_e32 v65, v7
	v_pk_add_f32 v[0:1], v[4:5], v[0:1] neg_lo:[0,1] neg_hi:[0,1]
	v_pk_mul_f32 v[4:5], v[128:129], v[64:65]
	v_mov_b32_e32 v6, v2
	v_mov_b32_e32 v7, v4
	v_mov_b32_e32 v4, v3
	v_mov_b32_e32 v128, v10
	s_waitcnt lgkmcnt(0)
	v_mov_b32_e32 v65, v8
	v_pk_add_f32 v[2:3], v[6:7], v[4:5] neg_lo:[0,1] neg_hi:[0,1]
	v_pk_mul_f32 v[4:5], v[128:129], v[64:65]
	v_mov_b32_e32 v128, v11
	ds_read2st64_b32 v[10:11], v161 offset0:240 offset1:244
	v_mov_b32_e32 v65, v9
	v_pk_mul_f32 v[6:7], v[128:129], v[64:65]
	v_mov_b32_e32 v8, v4
	v_mov_b32_e32 v9, v6
	v_mov_b32_e32 v6, v5
	v_mov_b32_e32 v128, v12
	s_waitcnt lgkmcnt(0)
	v_mov_b32_e32 v65, v10
	v_pk_add_f32 v[4:5], v[8:9], v[6:7] neg_lo:[0,1] neg_hi:[0,1]
	v_pk_mul_f32 v[6:7], v[128:129], v[64:65]
	v_mov_b32_e32 v128, v13
	ds_read2st64_b32 v[12:13], v161 offset0:248 offset1:252
	v_mov_b32_e32 v65, v11
	v_pk_mul_f32 v[8:9], v[128:129], v[64:65]
	v_mov_b32_e32 v10, v6
	v_mov_b32_e32 v11, v8
	v_mov_b32_e32 v8, v7
	v_pk_add_f32 v[6:7], v[10:11], v[8:9] neg_lo:[0,1] neg_hi:[0,1]
	s_waitcnt lgkmcnt(0)
; __device__ __forceinline__ unsigned cvt_pk_bf16(float lo, float hi) { unsigned r; asm volatile("v_cvt_pk_bf16_f32 %0, %1, %2" : "=v"(r) : "v"(lo), "v"(hi)); return r; }
; __device__ __forceinline__ void phase_attn(const Params& p, unsigned char* lds) {
;     ...
;                 for (int i = 0; i < 16; ++i) { const float o = ot[vb][i] * inv - lam * ex[(vb * 16 + i) * 256 + qsub * 64 + lane]; ot[vb][i] = o; sq += o * o; }
;             sq += __shfl_xor(sq, 32);
;             const float rs = rsqrtf(sq * (1.0f / 128.0f) + 1e-5f) * (1.0f - LINIT);
;             u16* orow = O + qrow * 2048 + 128 * h;
; #pragma unroll
;             for (int vb = 0; vb < 4; ++vb)
; #pragma unroll
;                 for (int i4 = 0; i4 < 4; ++i4) { const int v0 = 32 * vb + 8 * i4 + 4 * g; const f32x4 sg = *(const f32x4*)(p.diff_subln_g + v0);
;                     u32x2 o; o[0] = cvt_pk_bf16(ot[vb][4 * i4] * rs * sg[0], ot[vb][4 * i4 + 1] * rs * sg[1]); o[1] = cvt_pk_bf16(ot[vb][4 * i4 + 2] * rs * sg[2], ot[vb][4 * i4 + 3] * rs * sg[3]);
;                     *(u32x2*)(orow + v0) = o; }
	v_pk_mul_f32 v[8:9], v[142:143], v[12:13]
	global_load_dwordx4 v[172:175], v[140:141], off
	global_load_dwordx4 v[176:179], v[140:141], off offset:32
	global_load_dwordx4 v[180:183], v[140:141], off offset:64
	global_load_dwordx4 v[184:187], v[140:141], off offset:96
	global_load_dwordx4 v[188:191], v[140:141], off offset:128
	global_load_dwordx4 v[192:195], v[140:141], off offset:160
	global_load_dwordx4 v[196:199], v[140:141], off offset:192
	global_load_dwordx4 v[200:203], v[140:141], off offset:224
	global_load_dwordx4 v[204:207], v[140:141], off offset:256
	global_load_dwordx4 v[208:211], v[140:141], off offset:288
	global_load_dwordx4 v[212:215], v[140:141], off offset:320
	global_load_dwordx4 v[216:219], v[140:141], off offset:352
	global_load_dwordx4 v[220:223], v[140:141], off offset:384
	global_load_dwordx4 v[224:227], v[140:141], off offset:416
	global_load_dwordx4 v[228:231], v[140:141], off offset:448
	global_load_dwordx4 v[232:235], v[140:141], off offset:480
	v_pk_fma_f32 v[8:9], v[14:15], v[64:65], v[8:9] op_sel_hi:[1,0,1] neg_lo:[0,0,1] neg_hi:[0,0,1]
	v_mul_f32_e32 v64, v48, v48
	v_fmac_f32_e32 v64, v49, v49
	v_fmac_f32_e32 v64, v50, v50
	v_fmac_f32_e32 v64, v66, v66
	v_fmac_f32_e32 v64, v51, v51
	v_fmac_f32_e32 v64, v52, v52
	v_fmac_f32_e32 v64, v53, v53
	v_fmac_f32_e32 v64, v54, v54
	v_fmac_f32_e32 v64, v55, v55
	v_fmac_f32_e32 v64, v56, v56
	v_fmac_f32_e32 v64, v57, v57
	v_fmac_f32_e32 v64, v58, v58
	v_fmac_f32_e32 v64, v59, v59
	v_fmac_f32_e32 v64, v60, v60
	v_fmac_f32_e32 v64, v61, v61
	v_fmac_f32_e32 v64, v62, v62
	v_fmac_f32_e32 v64, v32, v32
	v_fmac_f32_e32 v64, v33, v33
	v_fmac_f32_e32 v64, v34, v34
	v_fmac_f32_e32 v64, v35, v35
	v_fmac_f32_e32 v64, v36, v36
	v_fmac_f32_e32 v64, v37, v37
	v_fmac_f32_e32 v64, v38, v38
	v_fmac_f32_e32 v64, v63, v63
	v_fmac_f32_e32 v64, v39, v39
	v_fmac_f32_e32 v64, v40, v40
	v_fmac_f32_e32 v64, v41, v41
	v_fmac_f32_e32 v64, v43, v43
	v_fmac_f32_e32 v64, v42, v42
	v_fmac_f32_e32 v64, v44, v44
	v_fmac_f32_e32 v64, v45, v45
	v_fmac_f32_e32 v64, v46, v46
	v_fmac_f32_e32 v64, v47, v47
	v_fmac_f32_e32 v64, v67, v67
	v_fmac_f32_e32 v64, v18, v18
	v_fmac_f32_e32 v64, v68, v68
	v_fmac_f32_e32 v64, v19, v19
	v_fmac_f32_e32 v64, v20, v20
	v_fmac_f32_e32 v64, v21, v21
	v_fmac_f32_e32 v64, v23, v23
	v_fmac_f32_e32 v64, v22, v22
	v_fmac_f32_e32 v64, v24, v24
	v_fmac_f32_e32 v64, v25, v25
	v_fmac_f32_e32 v64, v27, v27
	v_fmac_f32_e32 v64, v26, v26
	v_fmac_f32_e32 v64, v28, v28
	v_fmac_f32_e32 v64, v29, v29
	v_fmac_f32_e32 v64, v30, v30
	v_fmac_f32_e32 v64, v31, v31
	v_sub_f32_e32 v70, v16, v17
	v_fmac_f32_e32 v64, v69, v69
	v_fmac_f32_e32 v64, v70, v70
	v_fmac_f32_e32 v64, v72, v72
	v_fmac_f32_e32 v64, v71, v71
	v_pk_mul_f32 v[16:17], v[0:1], v[0:1]
	v_fmac_f32_e32 v64, v73, v73
	v_add_f32_e32 v16, v64, v16
	v_pk_mul_f32 v[74:75], v[2:3], v[2:3]
	v_add_f32_e32 v16, v16, v17
	v_add_f32_e32 v16, v16, v74
	v_pk_mul_f32 v[76:77], v[4:5], v[4:5]
	v_add_f32_e32 v16, v16, v75
	v_add_f32_e32 v16, v16, v76
	v_pk_mul_f32 v[78:79], v[6:7], v[6:7]
	v_add_f32_e32 v16, v16, v77
	v_add_f32_e32 v16, v16, v78
	v_pk_mul_f32 v[14:15], v[8:9], v[8:9]
	v_add_f32_e32 v16, v16, v79
	v_add_f32_e32 v14, v16, v14
	v_add_f32_e32 v14, v14, v15
	ds_bpermute_b32 v15, v158, v14
	s_waitcnt lgkmcnt(0)
	v_add_f32_e32 v14, v14, v15
	v_fmamk_f32 v14, v14, 0x3c000000, v171
	v_mul_f32_e32 v15, 0x4b800000, v14
	v_cmp_gt_f32_e32 vcc, s26, v14
	s_nop 1
	v_cndmask_b32_e32 v14, v14, v15, vcc
	v_rsq_f32_e32 v14, v14
	s_nop 0
	v_mul_f32_e32 v15, 0x45800000, v14
	v_cndmask_b32_e32 v14, v14, v15, vcc
	v_mul_f32_e32 v64, 0x3f24fd5c, v14
	v_mul_f32_e32 v16, v48, v64
	s_waitcnt vmcnt(0)
	v_mov_b32_e32 v10, v172
	v_mov_b32_e32 v11, v173
	v_mov_b32_e32 v12, v174
	v_mov_b32_e32 v13, v175
	v_mul_f32_e32 v10, v10, v16
	v_mul_f32_e32 v16, v49, v64
	v_lshlrev_b64 v[14:15], 12, v[150:151]
	v_mul_f32_e32 v11, v11, v16
	v_lshl_add_u64 v[14:15], s[22:23], 0, v[14:15]
	v_cvt_pk_bf16_f32 v16, v10, v11
	v_mul_f32_e32 v10, v50, v64
	v_mul_f32_e32 v11, v66, v64
	v_lshl_add_u64 v[14:15], v[14:15], 0, s[12:13]
	v_mul_f32_e32 v10, v12, v10
	v_mul_f32_e32 v11, v13, v11
	v_cvt_pk_bf16_f32 v17, v10, v11
	v_lshl_add_u64 v[10:11], v[14:15], 0, v[148:149]
	global_store_dwordx2 v[10:11], v[16:17], off
	v_mov_b32_e32 v12, v176
	v_mov_b32_e32 v13, v177
	v_mov_b32_e32 v14, v178
	v_mov_b32_e32 v15, v179
	v_mul_f32_e32 v16, v51, v64
	v_mul_f32_e32 v17, v37, v64
	v_mul_f32_e32 v18, v18, v64
	v_mul_f32_e32 v1, v1, v64
	v_mul_f32_e32 v0, v0, v64
	v_mul_f32_e32 v12, v12, v16
	v_mul_f32_e32 v16, v52, v64
	v_mul_f32_e32 v13, v13, v16
	v_cvt_pk_bf16_f32 v12, v12, v13
	v_mul_f32_e32 v13, v53, v64
	v_mul_f32_e32 v13, v14, v13
	v_mul_f32_e32 v14, v54, v64
	v_mul_f32_e32 v14, v15, v14
	v_cvt_pk_bf16_f32 v13, v13, v14
	global_store_dwordx2 v[10:11], v[12:13], off offset:16
	v_mov_b32_e32 v12, v180
	v_mov_b32_e32 v13, v181
	v_mov_b32_e32 v14, v182
	v_mov_b32_e32 v15, v183
	v_mul_f32_e32 v16, v55, v64
	v_mul_f32_e32 v12, v12, v16
	v_mul_f32_e32 v16, v56, v64
	v_mul_f32_e32 v13, v13, v16
	v_cvt_pk_bf16_f32 v12, v12, v13
	v_mul_f32_e32 v13, v57, v64
	v_mul_f32_e32 v13, v14, v13
	v_mul_f32_e32 v14, v58, v64
	v_mul_f32_e32 v14, v15, v14
	v_cvt_pk_bf16_f32 v13, v13, v14
	global_store_dwordx2 v[10:11], v[12:13], off offset:32
	v_mov_b32_e32 v12, v184
	v_mov_b32_e32 v13, v185
	v_mov_b32_e32 v14, v186
	v_mov_b32_e32 v15, v187
	v_mul_f32_e32 v16, v59, v64
	v_mul_f32_e32 v12, v16, v12
	v_mul_f32_e32 v16, v60, v64
	v_mul_f32_e32 v13, v16, v13
	v_cvt_pk_bf16_f32 v12, v12, v13
; __device__ __forceinline__ unsigned cvt_pk_bf16(float lo, float hi) { unsigned r; asm volatile("v_cvt_pk_bf16_f32 %0, %1, %2" : "=v"(r) : "v"(lo), "v"(hi)); return r; }
; __device__ __forceinline__ void phase_attn(const Params& p, unsigned char* lds) {
;     ...
; #pragma unroll
;             for (int vb = 0; vb < 4; ++vb)
; #pragma unroll
;                 for (int i4 = 0; i4 < 4; ++i4) { const int v0 = 32 * vb + 8 * i4 + 4 * g; const f32x4 sg = *(const f32x4*)(p.diff_subln_g + v0);
;                     u32x2 o; o[0] = cvt_pk_bf16(ot[vb][4 * i4] * rs * sg[0], ot[vb][4 * i4 + 1] * rs * sg[1]); o[1] = cvt_pk_bf16(ot[vb][4 * i4 + 2] * rs * sg[2], ot[vb][4 * i4 + 3] * rs * sg[3]);
;                     *(u32x2*)(orow + v0) = o; }
	v_mul_f32_e32 v13, v61, v64
	v_mul_f32_e32 v13, v13, v14
	v_mul_f32_e32 v14, v62, v64
	v_mul_f32_e32 v14, v14, v15
	v_cvt_pk_bf16_f32 v13, v13, v14
	global_store_dwordx2 v[10:11], v[12:13], off offset:48
	v_mov_b32_e32 v12, v188
	v_mov_b32_e32 v13, v189
	v_mov_b32_e32 v14, v190
	v_mov_b32_e32 v15, v191
	v_mul_f32_e32 v16, v32, v64
	v_mul_f32_e32 v32, v38, v64
	v_mul_f32_e32 v12, v16, v12
	v_mul_f32_e32 v16, v33, v64
	v_mul_f32_e32 v13, v16, v13
	v_cvt_pk_bf16_f32 v12, v12, v13
	v_mul_f32_e32 v13, v34, v64
	v_mul_f32_e32 v13, v13, v14
	v_mul_f32_e32 v14, v35, v64
	v_mul_f32_e32 v14, v14, v15
	v_cvt_pk_bf16_f32 v13, v13, v14
	global_store_dwordx2 v[10:11], v[12:13], off offset:64
	v_mov_b32_e32 v12, v192
	v_mov_b32_e32 v13, v193
	v_mov_b32_e32 v14, v194
	v_mov_b32_e32 v15, v195
	v_mul_f32_e32 v16, v36, v64
	v_mul_f32_e32 v33, v63, v64
	v_mul_f32_e32 v12, v16, v12
	v_mul_f32_e32 v13, v17, v13
	v_mul_f32_e32 v14, v32, v14
	v_mul_f32_e32 v15, v33, v15
	v_cvt_pk_bf16_f32 v12, v12, v13
	v_cvt_pk_bf16_f32 v13, v14, v15
	global_store_dwordx2 v[10:11], v[12:13], off offset:80
	v_mov_b32_e32 v12, v196
	v_mov_b32_e32 v13, v197
	v_mov_b32_e32 v14, v198
	v_mov_b32_e32 v15, v199
	v_mul_f32_e32 v16, v39, v64
	v_mul_f32_e32 v17, v40, v64
	v_mul_f32_e32 v32, v41, v64
	v_mul_f32_e32 v33, v43, v64
	v_mul_f32_e32 v12, v16, v12
	v_mul_f32_e32 v13, v17, v13
	v_mul_f32_e32 v14, v32, v14
	v_mul_f32_e32 v15, v33, v15
	v_cvt_pk_bf16_f32 v12, v12, v13
	v_cvt_pk_bf16_f32 v13, v14, v15
	global_store_dwordx2 v[10:11], v[12:13], off offset:96
	v_mov_b32_e32 v12, v200
	v_mov_b32_e32 v13, v201
	v_mov_b32_e32 v14, v202
	v_mov_b32_e32 v15, v203
	v_mul_f32_e32 v16, v42, v64
	v_mul_f32_e32 v17, v44, v64
	v_mul_f32_e32 v32, v45, v64
	v_mul_f32_e32 v33, v46, v64
	v_mul_f32_e32 v12, v16, v12
	v_mul_f32_e32 v13, v17, v13
	v_mul_f32_e32 v14, v32, v14
	v_mul_f32_e32 v15, v33, v15
	v_cvt_pk_bf16_f32 v12, v12, v13
	v_cvt_pk_bf16_f32 v13, v14, v15
	global_store_dwordx2 v[10:11], v[12:13], off offset:112
	v_mov_b32_e32 v12, v204
	v_mov_b32_e32 v13, v205
	v_mov_b32_e32 v14, v206
	v_mov_b32_e32 v15, v207
	v_mul_f32_e32 v16, v47, v64
	v_mul_f32_e32 v17, v67, v64
	v_mul_f32_e32 v32, v68, v64
	v_mul_f32_e32 v12, v16, v12
	v_mul_f32_e32 v13, v17, v13
	v_mul_f32_e32 v14, v18, v14
	v_mul_f32_e32 v15, v32, v15
	v_cvt_pk_bf16_f32 v12, v12, v13
	v_cvt_pk_bf16_f32 v13, v14, v15
	global_store_dwordx2 v[10:11], v[12:13], off offset:128
	v_mov_b32_e32 v12, v208
	v_mov_b32_e32 v13, v209
	v_mov_b32_e32 v14, v210
	v_mov_b32_e32 v15, v211
	v_mul_f32_e32 v16, v19, v64
	v_mul_f32_e32 v17, v20, v64
	v_mul_f32_e32 v18, v21, v64
	v_mul_f32_e32 v19, v23, v64
	v_mul_f32_e32 v12, v16, v12
	v_mul_f32_e32 v13, v17, v13
	v_mul_f32_e32 v14, v18, v14
	v_mul_f32_e32 v15, v19, v15
	v_cvt_pk_bf16_f32 v12, v12, v13
	v_cvt_pk_bf16_f32 v13, v14, v15
	global_store_dwordx2 v[10:11], v[12:13], off offset:144
	v_mov_b32_e32 v12, v212
	v_mov_b32_e32 v13, v213
	v_mov_b32_e32 v14, v214
	v_mov_b32_e32 v15, v215
	v_mul_f32_e32 v16, v22, v64
	v_mul_f32_e32 v17, v24, v64
	v_mul_f32_e32 v18, v25, v64
	v_mul_f32_e32 v19, v27, v64
	v_mul_f32_e32 v12, v16, v12
	v_mul_f32_e32 v13, v17, v13
	v_mul_f32_e32 v14, v18, v14
	v_mul_f32_e32 v15, v19, v15
	v_cvt_pk_bf16_f32 v12, v12, v13
	v_cvt_pk_bf16_f32 v13, v14, v15
	global_store_dwordx2 v[10:11], v[12:13], off offset:160
	v_mov_b32_e32 v12, v216
	v_mov_b32_e32 v13, v217
	v_mov_b32_e32 v14, v218
	v_mov_b32_e32 v15, v219
	v_mul_f32_e32 v16, v26, v64
	v_mul_f32_e32 v17, v28, v64
	v_mul_f32_e32 v18, v29, v64
	v_mul_f32_e32 v19, v30, v64
	v_mul_f32_e32 v12, v16, v12
	v_mul_f32_e32 v13, v17, v13
	v_mul_f32_e32 v14, v18, v14
	v_mul_f32_e32 v15, v19, v15
	v_cvt_pk_bf16_f32 v12, v12, v13
	v_cvt_pk_bf16_f32 v13, v14, v15
	global_store_dwordx2 v[10:11], v[12:13], off offset:176
	v_mov_b32_e32 v12, v220
	v_mov_b32_e32 v13, v221
	v_mov_b32_e32 v14, v222
	v_mov_b32_e32 v15, v223
	v_mul_f32_e32 v16, v31, v64
	v_mul_f32_e32 v17, v69, v64
	v_mul_f32_e32 v18, v70, v64
	v_mul_f32_e32 v19, v72, v64
	v_mul_f32_e32 v12, v16, v12
	v_mul_f32_e32 v13, v17, v13
	v_mul_f32_e32 v14, v18, v14
	v_mul_f32_e32 v15, v19, v15
	v_cvt_pk_bf16_f32 v12, v12, v13
	v_cvt_pk_bf16_f32 v13, v14, v15
	global_store_dwordx2 v[10:11], v[12:13], off offset:192
	v_mov_b32_e32 v12, v224
	v_mov_b32_e32 v13, v225
	v_mov_b32_e32 v14, v226
	v_mov_b32_e32 v15, v227
	v_mul_f32_e32 v16, v71, v64
	v_mul_f32_e32 v17, v73, v64
	v_mul_f32_e32 v1, v1, v15
	v_mul_f32_e32 v12, v16, v12
	v_mul_f32_e32 v13, v17, v13
	v_mul_f32_e32 v14, v0, v14
	v_cvt_pk_bf16_f32 v0, v12, v13
	v_cvt_pk_bf16_f32 v1, v14, v1
	global_store_dwordx2 v[10:11], v[0:1], off offset:208
	v_mov_b32_e32 v12, v228
	v_mov_b32_e32 v13, v229
	v_mov_b32_e32 v14, v230
	v_mov_b32_e32 v15, v231
	v_mul_f32_e32 v0, v2, v64
	v_mul_f32_e32 v1, v3, v64
	v_mul_f32_e32 v2, v4, v64
	v_mul_f32_e32 v3, v5, v64
	v_mul_f32_e32 v4, v6, v64
	v_mul_f32_e32 v5, v7, v64
	v_mul_f32_e32 v6, v8, v64
	v_mul_f32_e32 v7, v9, v64
	v_mul_f32_e32 v0, v0, v12
	v_mul_f32_e32 v1, v1, v13
	v_mul_f32_e32 v2, v2, v14
	v_mul_f32_e32 v3, v3, v15
	v_cvt_pk_bf16_f32 v0, v0, v1
	v_cvt_pk_bf16_f32 v1, v2, v3
	global_store_dwordx2 v[10:11], v[0:1], off offset:224
	v_mov_b32_e32 v0, v232
	v_mov_b32_e32 v1, v233
	v_mov_b32_e32 v2, v234
	v_mov_b32_e32 v3, v235
	v_mul_f32_e32 v0, v4, v0
	v_mul_f32_e32 v1, v5, v1
	v_mul_f32_e32 v2, v6, v2
	v_mul_f32_e32 v3, v7, v3
	v_cvt_pk_bf16_f32 v0, v0, v1
	v_cvt_pk_bf16_f32 v1, v2, v3
	global_store_dwordx2 v[10:11], v[0:1], off offset:240
	s_branch .LBB0_2019
